# grid-barrier seams: the block that completes the top-level count releases all per-XCD generation words itself (no relay hop through each XCD's last arriver)
# speedup vs baseline: 1.0300x; 1.0033x over previous
; __device__ __forceinline__ unsigned xb_ld(unsigned* p)              { return __hip_atomic_load(p, __ATOMIC_RELAXED, __HIP_MEMORY_SCOPE_AGENT); }
; __device__ __forceinline__ unsigned xb_add(unsigned* p, unsigned v) { return __hip_atomic_fetch_add(p, v, __ATOMIC_RELAXED, __HIP_MEMORY_SCOPE_AGENT); }
; #define XB_SPIN(cond, bar) do { unsigned _sp = 0; while (cond) { __builtin_amdgcn_s_sleep(1); \
;     if ((++_sp & 255u) == 0u) { if (xb_ld(&(bar)[XB_TMO])) break; if (_sp > XB_SPIN_CAP) { atomicAdd(&(bar)[XB_TMO], 1u); break; } } } } while (0)
; __device__ __forceinline__ void xcd_barrier(const XcdBarrier& b) {
;     ...
;         if (old + 1u == (gen + 1u) * nloc) {
;             __builtin_amdgcn_fence(__ATOMIC_RELEASE, "agent");
;             asm volatile("s_waitcnt vmcnt(0)" ::: "memory");
;             const unsigned og = xb_add(&bar[XB_TOP], 1u);
;             const unsigned tg = og / nx;
;             if (og + 1u == (tg + 1u) * nx) xb_add(&bar[XB_TOPGEN], 1u);
;             else XB_SPIN(xb_ld(&bar[XB_TOPGEN]) == tg, bar);
;             __builtin_amdgcn_fence(__ATOMIC_ACQUIRE, "agent");
;             xb_add(&bar[XB_XGEN(b.x)], 1u);
;             asm volatile("s_waitcnt vmcnt(0)" ::: "memory");
.LBB0_182:
	s_or_b64 exec, exec, s[10:11]
	s_and_saveexec_b64 s[2:3], s[12:13]
	s_cbranch_execz .LBB0_184
	v_mov_b32_e32 v2, 1
	global_atomic_add v[0:1], v2, off
	s_add_u32 s98, s66, 0x2400
	s_addc_u32 s99, s67, 0
	v_mov_b32_e32 v3, 0
	global_atomic_add v3, v2, s[98:99]
	global_atomic_add v3, v2, s[98:99] offset:256
	global_atomic_add v3, v2, s[98:99] offset:512
	global_atomic_add v3, v2, s[98:99] offset:768
	global_atomic_add v3, v2, s[98:99] offset:1024
	global_atomic_add v3, v2, s[98:99] offset:1280
	global_atomic_add v3, v2, s[98:99] offset:1536
	global_atomic_add v3, v2, s[98:99] offset:1792
.LBB0_184:
	s_or_b64 exec, exec, s[2:3]
	s_mov_b64 s[2:3], exec
	v_mbcnt_lo_u32_b32 v0, s2, 0
	v_mbcnt_hi_u32_b32 v0, s3, v0
	v_cmp_eq_u32_e32 vcc, 0, v0
	s_waitcnt vmcnt(0)
	s_and_saveexec_b64 s[8:9], vcc
	s_cbranch_execz .LBB0_186
	s_bcnt1_i32_b64 s2, s[2:3]
	v_mov_b32_e32 v0, 0
	v_mov_b32_e32 v1, s2
	s_nop 0

; __device__ __forceinline__ unsigned xb_ld(unsigned* p)              { return __hip_atomic_load(p, __ATOMIC_RELAXED, __HIP_MEMORY_SCOPE_AGENT); }
; __device__ __forceinline__ unsigned xb_add(unsigned* p, unsigned v) { return __hip_atomic_fetch_add(p, v, __ATOMIC_RELAXED, __HIP_MEMORY_SCOPE_AGENT); }
; #define XB_SPIN(cond, bar) do { unsigned _sp = 0; while (cond) { __builtin_amdgcn_s_sleep(1); \
;     if ((++_sp & 255u) == 0u) { if (xb_ld(&(bar)[XB_TMO])) break; if (_sp > XB_SPIN_CAP) { atomicAdd(&(bar)[XB_TMO], 1u); break; } } } } while (0)
; __device__ __forceinline__ void xcd_barrier(const XcdBarrier& b) {
;     ...
;         if (old + 1u == (gen + 1u) * nloc) {
;             __builtin_amdgcn_fence(__ATOMIC_RELEASE, "agent");
;             asm volatile("s_waitcnt vmcnt(0)" ::: "memory");
;             const unsigned og = xb_add(&bar[XB_TOP], 1u);
;             const unsigned tg = og / nx;
;             if (og + 1u == (tg + 1u) * nx) xb_add(&bar[XB_TOPGEN], 1u);
;             else XB_SPIN(xb_ld(&bar[XB_TOPGEN]) == tg, bar);
;             __builtin_amdgcn_fence(__ATOMIC_ACQUIRE, "agent");
;             xb_add(&bar[XB_XGEN(b.x)], 1u);
;             asm volatile("s_waitcnt vmcnt(0)" ::: "memory");
.LBB0_394:
	s_or_b64 exec, exec, s[4:5]
	s_and_saveexec_b64 s[4:5], s[8:9]
	s_cbranch_execz .LBB0_396
	v_mov_b32_e32 v2, 1
	global_atomic_add v[0:1], v2, off
	s_add_u32 s98, s66, 0x2400
	s_addc_u32 s99, s67, 0
	v_mov_b32_e32 v3, 0
	global_atomic_add v3, v2, s[98:99]
	global_atomic_add v3, v2, s[98:99] offset:256
	global_atomic_add v3, v2, s[98:99] offset:512
	global_atomic_add v3, v2, s[98:99] offset:768
	global_atomic_add v3, v2, s[98:99] offset:1024
	global_atomic_add v3, v2, s[98:99] offset:1280
	global_atomic_add v3, v2, s[98:99] offset:1536
	global_atomic_add v3, v2, s[98:99] offset:1792
.LBB0_396:
	s_or_b64 exec, exec, s[4:5]
	s_mov_b64 s[4:5], exec
	v_mbcnt_lo_u32_b32 v0, s4, 0
	v_mbcnt_hi_u32_b32 v0, s5, v0
	v_cmp_eq_u32_e32 vcc, 0, v0
	s_waitcnt vmcnt(0)
	s_and_saveexec_b64 s[6:7], vcc
	s_cbranch_execz .LBB0_398
	s_bcnt1_i32_b64 s4, s[4:5]
	v_mov_b32_e32 v0, 0x2000
	v_mov_b32_e32 v1, s4
	s_nop 0

; __device__ __forceinline__ unsigned xb_ld(unsigned* p)              { return __hip_atomic_load(p, __ATOMIC_RELAXED, __HIP_MEMORY_SCOPE_AGENT); }
; __device__ __forceinline__ unsigned xb_add(unsigned* p, unsigned v) { return __hip_atomic_fetch_add(p, v, __ATOMIC_RELAXED, __HIP_MEMORY_SCOPE_AGENT); }
; #define XB_SPIN(cond, bar) do { unsigned _sp = 0; while (cond) { __builtin_amdgcn_s_sleep(1); \
;     if ((++_sp & 255u) == 0u) { if (xb_ld(&(bar)[XB_TMO])) break; if (_sp > XB_SPIN_CAP) { atomicAdd(&(bar)[XB_TMO], 1u); break; } } } } while (0)
; __device__ __forceinline__ void xcd_barrier(const XcdBarrier& b) {
;     ...
;         if (old + 1u == (gen + 1u) * nloc) {
;             __builtin_amdgcn_fence(__ATOMIC_RELEASE, "agent");
;             asm volatile("s_waitcnt vmcnt(0)" ::: "memory");
;             const unsigned og = xb_add(&bar[XB_TOP], 1u);
;             const unsigned tg = og / nx;
;             if (og + 1u == (tg + 1u) * nx) xb_add(&bar[XB_TOPGEN], 1u);
;             else XB_SPIN(xb_ld(&bar[XB_TOPGEN]) == tg, bar);
;             __builtin_amdgcn_fence(__ATOMIC_ACQUIRE, "agent");
;             xb_add(&bar[XB_XGEN(b.x)], 1u);
;             asm volatile("s_waitcnt vmcnt(0)" ::: "memory");
.LBB0_514:
	s_or_b64 exec, exec, s[8:9]
	s_and_saveexec_b64 s[2:3], s[10:11]
	s_cbranch_execz .LBB0_516
	v_mov_b32_e32 v2, 1
	global_atomic_add v[0:1], v2, off
	s_add_u32 s98, s66, 0x2400
	s_addc_u32 s99, s67, 0
	v_mov_b32_e32 v3, 0
	global_atomic_add v3, v2, s[98:99]
	global_atomic_add v3, v2, s[98:99] offset:256
	global_atomic_add v3, v2, s[98:99] offset:512
	global_atomic_add v3, v2, s[98:99] offset:768
	global_atomic_add v3, v2, s[98:99] offset:1024
	global_atomic_add v3, v2, s[98:99] offset:1280
	global_atomic_add v3, v2, s[98:99] offset:1536
	global_atomic_add v3, v2, s[98:99] offset:1792
.LBB0_516:
	s_or_b64 exec, exec, s[2:3]
	s_mov_b64 s[2:3], exec
	v_mbcnt_lo_u32_b32 v0, s2, 0
	v_mbcnt_hi_u32_b32 v0, s3, v0
	v_cmp_eq_u32_e32 vcc, 0, v0
	s_waitcnt vmcnt(0)
	s_and_saveexec_b64 s[6:7], vcc
	s_cbranch_execz .LBB0_518
	s_bcnt1_i32_b64 s2, s[2:3]
	v_mov_b32_e32 v0, 0
	v_mov_b32_e32 v1, s2
	s_nop 0

; __device__ __forceinline__ unsigned xb_ld(unsigned* p)              { return __hip_atomic_load(p, __ATOMIC_RELAXED, __HIP_MEMORY_SCOPE_AGENT); }
; __device__ __forceinline__ unsigned xb_add(unsigned* p, unsigned v) { return __hip_atomic_fetch_add(p, v, __ATOMIC_RELAXED, __HIP_MEMORY_SCOPE_AGENT); }
; #define XB_SPIN(cond, bar) do { unsigned _sp = 0; while (cond) { __builtin_amdgcn_s_sleep(1); \
;     if ((++_sp & 255u) == 0u) { if (xb_ld(&(bar)[XB_TMO])) break; if (_sp > XB_SPIN_CAP) { atomicAdd(&(bar)[XB_TMO], 1u); break; } } } } while (0)
; __device__ __forceinline__ void xcd_barrier(const XcdBarrier& b) {
;     ...
;         if (old + 1u == (gen + 1u) * nloc) {
;             __builtin_amdgcn_fence(__ATOMIC_RELEASE, "agent");
;             asm volatile("s_waitcnt vmcnt(0)" ::: "memory");
;             const unsigned og = xb_add(&bar[XB_TOP], 1u);
;             const unsigned tg = og / nx;
;             if (og + 1u == (tg + 1u) * nx) xb_add(&bar[XB_TOPGEN], 1u);
;             else XB_SPIN(xb_ld(&bar[XB_TOPGEN]) == tg, bar);
;             __builtin_amdgcn_fence(__ATOMIC_ACQUIRE, "agent");
;             xb_add(&bar[XB_XGEN(b.x)], 1u);
;             asm volatile("s_waitcnt vmcnt(0)" ::: "memory");
.LBB0_1087:
	s_or_b64 exec, exec, s[6:7]
	s_and_saveexec_b64 s[6:7], s[10:11]
	s_cbranch_execz .LBB0_1089
	v_mov_b32_e32 v2, 1
	global_atomic_add v[0:1], v2, off
	s_add_u32 s98, s66, 0x2400
	s_addc_u32 s99, s67, 0
	v_mov_b32_e32 v3, 0
	global_atomic_add v3, v2, s[98:99]
	global_atomic_add v3, v2, s[98:99] offset:256
	global_atomic_add v3, v2, s[98:99] offset:512
	global_atomic_add v3, v2, s[98:99] offset:768
	global_atomic_add v3, v2, s[98:99] offset:1024
	global_atomic_add v3, v2, s[98:99] offset:1280
	global_atomic_add v3, v2, s[98:99] offset:1536
	global_atomic_add v3, v2, s[98:99] offset:1792
.LBB0_1089:
	s_or_b64 exec, exec, s[6:7]
	s_mov_b64 s[6:7], exec
	v_mbcnt_lo_u32_b32 v0, s6, 0
	v_mbcnt_hi_u32_b32 v0, s7, v0
	v_cmp_eq_u32_e32 vcc, 0, v0
	s_waitcnt vmcnt(0)
	s_and_saveexec_b64 s[8:9], vcc
	s_cbranch_execz .LBB0_1091
	s_bcnt1_i32_b64 s6, s[6:7]
	v_mov_b32_e32 v0, 0x2000
	v_mov_b32_e32 v1, s6
	s_nop 0
